# MoBA unit prologue: query tile, k-block means and bias entry requested together; next work-queue unit reserved ahead
# speedup vs baseline: 1.0093x; 1.0093x over previous
; __device__ __forceinline__ void lds_barrier() { asm volatile("s_waitcnt lgkmcnt(0)" ::: "memory"); __builtin_amdgcn_s_barrier(); asm volatile("" ::: "memory"); }
; __global__ void __launch_bounds__(NTHREADS, 2) mega(Args a) {
;     ...
;         for (int qo = 0; qo < 8; ++qo) {
;             const int qx = (int)((xcc + (unsigned)qo) & 7u);
;             for (;;) {
;                 lds_barrier();
;                 if (tidA == 0) *uslot = atomicAdd(cnt + qx, 1u);
;                 lds_barrier();
;                 const int k = (int)*uslot;
;                 if (k >= 128 || (a.probe & 16)) break;
;                 const int qt = 31 - (k & 31), bh = qx + 8 * (k >> 5), b = bh >> 3, h = bh & 7;
;                 const bf16_t* base = proj + (size_t)(b * SEQ) * NIN + h * 128;
.LBB0_1138:
	s_mov_b32 s59, 0
	s_and_b32 s8, s48, 7
	s_lshl_b32 s18, s8, 8
	s_add_i32 s8, s49, s33
	s_and_b32 s50, s8, 7
	s_lshl_b32 s8, s50, 2
	s_add_u32 s26, s2, s8
	s_addc_u32 s27, s3, 0
	s_lshl_b32 s8, s50, 8
	s_add_u32 s51, s16, s8
	s_addc_u32 s52, s17, 0
	v_lshl_add_u64 v[150:151], v[130:131], 0, s[18:19]
	v_lshl_add_u64 v[152:153], v[132:133], 0, s[18:19]
	v_lshl_add_u64 v[154:155], v[134:135], 0, s[18:19]
	v_lshl_add_u64 v[156:157], v[136:137], 0, s[18:19]
	s_branch .LBB0_1141

; __device__ __forceinline__ void lds_barrier() { asm volatile("s_waitcnt lgkmcnt(0)" ::: "memory"); __builtin_amdgcn_s_barrier(); asm volatile("" ::: "memory"); }
; __global__ void __launch_bounds__(NTHREADS, 2) mega(Args a) {
;     ...
;             for (;;) {
;                 lds_barrier();
;                 if (tidA == 0) *uslot = atomicAdd(cnt + qx, 1u);
.LBB0_1141:
	s_waitcnt lgkmcnt(0)
	s_barrier
	s_and_saveexec_b64 s[8:9], s[4:5]
	s_cbranch_execz .LBB0_1145
	s_cmp_eq_u32 s59, 0
	s_cbranch_scc1 .Lpop_now
	s_waitcnt vmcnt(0)
	v_mov_b32_e32 v1, s43
	ds_write_b32 v1, v243
	s_branch .LBB0_1145
.Lpop_now:
	s_mov_b64 s[28:29], exec
	v_mbcnt_lo_u32_b32 v0, s28, 0
	v_mbcnt_hi_u32_b32 v0, s29, v0
	v_cmp_eq_u32_e32 vcc, 0, v0
	s_and_saveexec_b64 s[10:11], vcc
	s_cbranch_execz .LBB0_1144
	s_bcnt1_i32_b64 s18, s[28:29]
	v_mov_b32_e32 v1, s18
	global_atomic_add v1, v115, v1, s[26:27] sc0

; #define LAS __attribute__((address_space(3)))
; __device__ __forceinline__ void lds_barrier() { asm volatile("s_waitcnt lgkmcnt(0)" ::: "memory"); __builtin_amdgcn_s_barrier(); asm volatile("" ::: "memory"); }
; template <bool MOBA>
; __device__ __forceinline__ void attn_unit(LAS unsigned char* lds, const bf16_t* Qp, int ldq, const bf16_t* Kp, const bf16_t* Vp, int ldkv, bf16_t* Op, int ldo, int qt, const float* kmean, const float* relb, const int tid) {
;     ...
;         for (int i = 0; i < 4; ++i) { const int id = tid + 512 * i, r = id >> 4, c = id & 15; *(LAS u32x4*)(lds + AT_KS + r * AT_PITCH + c * 16) = *(const u32x4*)(Qp + (size_t)r * ldq + c * 8); }
;         for (int i = tid; i < own * 128; i += 512) { const float* kp = kmean + (size_t)(i >> 7) * 512 + (i & 127); ((LAS float*)(lds + AT_KM))[i] = (kp[0] + kp[128]) + (kp[256] + kp[384]); }
;         if (tid < 128) { const int n = tid; int bk = n; if (n >= 16) { bk = 16 + (int)(logf((float)n / 16.f) / 2.0794415416798357f * 16.f); if (bk > 31) bk = 31; } ((LAS float*)(lds + AT_LUT))[tid] = relb[bk * 8] * L2E; }
; __global__ void __launch_bounds__(NTHREADS, 2) mega(Args a) {
;     ...
;                 if (tidA == 0) *uslot = atomicAdd(cnt + qx, 1u);
;                 lds_barrier();
;                 const int k = (int)*uslot;
;                 if (k >= 128 || (a.probe & 16)) break;
;                 const int qt = 31 - (k & 31), bh = qx + 8 * (k >> 5), b = bh >> 3, h = bh & 7;
;                 const bf16_t* base = proj + (size_t)(b * SEQ) * NIN + h * 128;
;                 attn_unit<true>(lds, base + (size_t)(qt * 128) * NIN, NIN, base + 1024, base + 2048, NIN, proj + (size_t)(b * SEQ + qt * 128) * NIN + h * 128, NIN, qt,
;                                 (const float*)(ws + WS_KMEAN) + (size_t)bh * 8192, AIN(I_RELB) + h, tidA);
.LBB0_1145:
	s_or_b64 exec, exec, s[8:9]
	s_waitcnt lgkmcnt(0)
	s_barrier
	v_mov_b32_e32 v0, s43
	ds_read_b32 v0, v0
	s_mov_b64 s[8:9], -1
	s_waitcnt lgkmcnt(0)
	v_cmp_lt_i32_e32 vcc, s42, v0
	s_or_b64 s[10:11], vcc, s[20:21]
	v_readfirstlane_b32 s18, v0
	s_and_b64 vcc, exec, s[10:11]
	s_cbranch_vccnz .LBB0_1140
	s_and_saveexec_b64 s[70:71], s[4:5]
	s_cbranch_execz .Lpop_ahead_skip
	v_mov_b32_e32 v244, 1
	global_atomic_add v243, v115, v244, s[26:27] sc0
.Lpop_ahead_skip:
	s_or_b64 exec, exec, s[70:71]
	s_mov_b32 s59, 1
	s_lshl_b32 s8, s18, 7
	s_and_b32 s8, s8, 0xfffff000
	s_not_b32 s34, s18
	s_andn2_b32 s53, 31, s18
	s_mul_i32 s10, s8, 0x5a00
	s_mul_hi_i32 s11, s8, 0x5a00
	s_add_u32 s28, s51, s10
	s_addc_u32 s29, s52, s11
	s_mul_i32 s8, s53, 0x2d0000
	s_add_u32 s30, s28, s8
	s_addc_u32 s31, s29, 0
	v_lshl_add_u64 v[8:9], s[30:31], 0, v[114:115]
	s_load_dwordx2 s[8:9], s[0:1], 0x60
	s_waitcnt lgkmcnt(0)
	s_barrier
	v_lshl_add_u64 v[0:1], v[8:9], 0, v[116:117]
	v_lshl_add_u64 v[4:5], v[8:9], 0, v[118:119]
	v_lshl_add_u64 v[10:11], v[8:9], 0, v[120:121]
	v_lshl_add_u64 v[12:13], v[8:9], 0, v[122:123]
	global_load_dwordx4 v[80:83], v[0:1], off
	global_load_dwordx4 v[84:87], v[4:5], off
	global_load_dwordx4 v[88:91], v[10:11], off
	global_load_dwordx4 v[92:95], v[12:13], off
	s_lshl_b32 s57, s50, 2
	s_add_u32 s8, s8, s57
	s_addc_u32 s9, s9, 0
	s_and_saveexec_b64 s[70:71], s[6:7]
	s_cbranch_execz .Lap1_nolut
	v_lshl_add_u64 v[96:97], v[128:129], 2, s[8:9]
	global_load_dword v96, v[96:97], off
.Lap1_nolut:
	s_or_b64 exec, exec, s[70:71]
	s_bfe_u32 s54, s34, 0x40001
	s_lshl_b32 s56, s54, 7
	v_readfirstlane_b32 s55, v112
	v_cmp_gt_i32_e32 vcc, s56, v112
	s_and_saveexec_b64 s[30:31], vcc
	s_cbranch_execz .LBB0_1156
	s_ashr_i32 s34, s18, 2
	s_and_b32 s34, s34, -8
	s_or_b32 s34, s34, s50
	s_ashr_i32 s35, s34, 31
	v_max_i32_e32 v2, s56, v113
	s_lshl_b64 s[34:35], s[34:35], 15
	v_add_u32_e32 v4, v2, v185
	v_lshl_add_u64 v[0:1], v[124:125], 0, s[34:35]
	v_cmp_lt_u32_e32 vcc, s44, v4
	s_mov_b64 s[36:37], -1
	v_mov_b32_e32 v2, v112
	v_mov_b32_e32 v3, v176
	s_and_saveexec_b64 s[34:35], vcc
	s_cbranch_execz .LBB0_1153
	v_lshrrev_b32_e32 v2, 9, v4
	v_add_u32_e32 v5, 1, v2
	v_and_b32_e32 v4, 0xfffffe, v5
	s_mov_b64 s[36:37], 0
	v_mov_b32_e32 v6, v4
	v_mov_b32_e32 v7, v186
	v_mov_b64_e32 v[2:3], v[112:113]

; #define LAS __attribute__((address_space(3)))
; __device__ __forceinline__ void lds_barrier() { asm volatile("s_waitcnt lgkmcnt(0)" ::: "memory"); __builtin_amdgcn_s_barrier(); asm volatile("" ::: "memory"); }
; template <bool MOBA>
; __device__ __forceinline__ void attn_unit(LAS unsigned char* lds, const bf16_t* Qp, int ldq, const bf16_t* Kp, const bf16_t* Vp, int ldkv, bf16_t* Op, int ldo, int qt, const float* kmean, const float* relb, const int tid) {
;     ...
;         for (int i = 0; i < 4; ++i) { const int id = tid + 512 * i, r = id >> 4, c = id & 15; *(LAS u32x4*)(lds + AT_KS + r * AT_PITCH + c * 16) = *(const u32x4*)(Qp + (size_t)r * ldq + c * 8); }
;         for (int i = tid; i < own * 128; i += 512) { const float* kp = kmean + (size_t)(i >> 7) * 512 + (i & 127); ((LAS float*)(lds + AT_KM))[i] = (kp[0] + kp[128]) + (kp[256] + kp[384]); }
;         if (tid < 128) { const int n = tid; int bk = n; if (n >= 16) { bk = 16 + (int)(logf((float)n / 16.f) / 2.0794415416798357f * 16.f); if (bk > 31) bk = 31; } ((LAS float*)(lds + AT_LUT))[tid] = relb[bk * 8] * L2E; }
;         lds_barrier();
;         { const int q = tid & 127, jg = tid >> 7;
.LBB0_1156:
	s_or_b64 exec, exec, s[30:31]
	s_and_saveexec_b64 s[30:31], s[6:7]
	s_cbranch_execz .LBB0_1158
	s_waitcnt vmcnt(0) lgkmcnt(0)
	v_mul_f32_e32 v0, 0x3fb8aa3b, v96
	ds_write_b32 v177, v0
.LBB0_1158:
	s_or_b64 exec, exec, s[30:31]
	v_add_u32_e32 v16, v171, v172
	v_add_u32_e32 v17, v171, v173
	v_add_u32_e32 v18, v171, v174
	v_add_u32_e32 v19, v171, v175
	s_waitcnt vmcnt(0)
	ds_write_b128 v16, v[80:83]
	ds_write_b128 v17, v[84:87]
	ds_write_b128 v18, v[88:91]
	ds_write_b128 v19, v[92:95]
	s_waitcnt lgkmcnt(0)
	s_barrier
	v_cmp_gt_i32_e32 vcc, s54, v178
	s_waitcnt lgkmcnt(0)
	s_and_saveexec_b64 s[8:9], vcc
	s_cbranch_execz .LBB0_1163
	s_mov_b64 s[30:31], 0
	v_mov_b32_e32 v0, v187
	v_mov_b32_e32 v1, v178
